# prompt attention K staging: g_k_nope gains loaded once per unit instead of every key tile; 8-lane sums of squares by DPP adds instead of 3 dependent ds_bpermute round trips
# speedup vs baseline: 1.0288x; 1.0040x over previous
.LBB0_865:
	s_or_b64 exec, exec, s[4:5]
	v_add_f32_e32 v44, v44, v48
	v_mul_f32_e32 v48, 0x4f800000, v44
	v_cmp_gt_f32_e32 vcc, s11, v44
	v_add_f32_e32 v46, v46, v47
	v_and_b32_e32 v25, 63, v59
	v_cndmask_b32_e32 v44, v44, v48, vcc
	v_sqrt_f32_e32 v48, v44
	v_lshlrev_b32_e32 v218, 8, v172
	s_lshl_b32 s25, s21, 1
	s_movk_i32 s4, 0x50
	v_add_u32_e32 v47, -1, v48
	v_fma_f32 v65, -v47, v48, v44
	v_cmp_ge_f32_e64 s[8:9], 0, v65
	v_add_u32_e32 v65, 1, v48
	v_readlane_b32 s36, v254, 28
	v_cndmask_b32_e64 v47, v48, v47, s[8:9]
	v_fma_f32 v48, -v65, v48, v44
	v_cmp_lt_f32_e64 s[8:9], 0, v48
	v_lshrrev_b32_e32 v61, 16, v38
	s_add_i32 s25, s25, 16
	v_cndmask_b32_e64 v47, v47, v65, s[8:9]
	v_mul_f32_e32 v48, 0x37800000, v47
	v_cndmask_b32_e32 v47, v47, v48, vcc
	v_mul_f32_e32 v48, 0x4f800000, v46
	v_cmp_gt_f32_e32 vcc, s11, v46
	v_cmp_class_f32_e64 s[8:9], v44, v192
	s_bitset1_b32 s18, 7
	v_cndmask_b32_e32 v46, v46, v48, vcc
	v_sqrt_f32_e32 v48, v46
	v_cndmask_b32_e64 v44, v47, v44, s[8:9]
	v_mul_f32_e32 v44, 0x41000000, v44
	s_or_b32 s26, s24, 31
	v_add_u32_e32 v47, -1, v48
	v_fma_f32 v65, -v47, v48, v46
	v_cmp_ge_f32_e64 s[8:9], 0, v65
	v_add_u32_e32 v65, 1, v48
	v_readlane_b32 s48, v254, 40
	v_cndmask_b32_e64 v47, v48, v47, s[8:9]
	v_fma_f32 v48, -v65, v48, v46
	v_cmp_lt_f32_e64 s[8:9], 0, v48
	v_perm_b32 v156, v61, v38, s22
	v_readlane_b32 s37, v254, 29
	v_cndmask_b32_e64 v47, v47, v65, s[8:9]
	v_mul_f32_e32 v48, 0x37800000, v47
	v_cndmask_b32_e32 v47, v47, v48, vcc
	v_cmp_class_f32_e32 vcc, v46, v192
	v_bfe_u32 v48, v59, 1, 1
	v_readlane_b32 s38, v254, 30
	v_cndmask_b32_e32 v46, v47, v46, vcc
	v_mul_f32_e32 v46, 0x40b504f3, v46
	v_mul_f32_e32 v15, v15, v46
	v_fmac_f32_e32 v15, v14, v44
	v_lshlrev_b32_e32 v14, 2, v55
	v_and_b32_e32 v14, 12, v14
	v_bfe_u32 v44, v59, 2, 2
	v_bitop3_b32 v46, v14, v51, v44 bitop3:0x36
	v_lshlrev_b32_e32 v207, 4, v46
	v_or_b32_e32 v46, 2, v51
	v_bitop3_b32 v46, v14, v46, v44 bitop3:0x36
	v_lshlrev_b32_e32 v208, 4, v46
	v_or_b32_e32 v46, 4, v51
	v_bitop3_b32 v46, v14, v46, v44 bitop3:0x36
	v_lshlrev_b32_e32 v209, 4, v46
	v_or_b32_e32 v46, 6, v51
	v_bitop3_b32 v14, v14, v46, v44 bitop3:0x36
	v_lshlrev_b32_e32 v210, 4, v14
	v_lshrrev_b32_e32 v14, 3, v25
	v_fmamk_f32 v46, v15, 0x3f828f5c, v193
	v_and_b32_e32 v15, 4, v14
	v_or_b32_e32 v47, v15, v44
	v_and_or_b32 v14, v14, 2, v48
	v_lshlrev_b32_e32 v25, 3, v25
	v_or_b32_e32 v15, 8, v15
	v_or_b32_e32 v48, 8, v14
	v_lshlrev_b32_e32 v211, 8, v47
	v_and_b32_e32 v47, 12, v59
	v_and_b32_e32 v213, 8, v25
	v_or_b32_e32 v25, v15, v44
	v_lshrrev_b32_e32 v15, 2, v15
	v_or_b32_e32 v59, v51, v47
	v_lshlrev_b32_e32 v214, 8, v25
	v_bitop3_b32 v25, v15, v48, v47 bitop3:0x36
	v_bitop3_b32 v65, v14, v59, 8 bitop3:0x36
	v_lshlrev_b32_e32 v215, 4, v25
	v_or_b32_e32 v25, 12, v14
	v_bitop3_b32 v14, v14, v59, 12 bitop3:0x36
	v_lshlrev_b32_e32 v216, 4, v14
	v_bitop3_b32 v14, v15, v25, v47 bitop3:0x36
	v_lshlrev_b32_e32 v217, 4, v14
	v_pk_mul_f32 v[14:15], v[24:25], v[16:17] op_sel_hi:[0,1]
	v_pk_mul_f32 v[8:9], v[8:9], v[14:15]
	v_pk_mul_f32 v[14:15], v[24:25], v[18:19] op_sel_hi:[0,1]
	v_pk_mul_f32 v[10:11], v[10:11], v[14:15]
	v_pk_mul_f32 v[14:15], v[24:25], v[20:21] op_sel_hi:[0,1]
	v_pk_mul_f32 v[14:15], v[4:5], v[14:15]
	v_pk_mul_f32 v[4:5], v[24:25], v[22:23] op_sel_hi:[0,1]
	v_pk_mul_f32 v[16:17], v[6:7], v[4:5]
	v_cvt_pk_bf16_f32 v4, v8, v9
	v_lshlrev_b32_e32 v8, 2, v172
	v_and_b32_e32 v8, 12, v8
	v_bfe_u32 v9, v172, 2, 2
	v_bitop3_b32 v8, v8, v45, v9 bitop3:0x36
	v_lshlrev_b32_e32 v219, 4, v8
	v_cvt_pk_bf16_f32 v5, v10, v11
	v_cvt_pk_bf16_f32 v6, v14, v15
	v_cvt_pk_bf16_f32 v7, v16, v17
	v_add3_u32 v8, 0, v219, v218
	ds_write_b128 v8, v[4:7]
	v_mul_lo_u32 v4, v174, s4
	s_lshl_b32 s4, s12, 1
	v_readlane_b32 s39, v254, 31
	v_readlane_b32 s40, v254, 32
	v_readlane_b32 s41, v254, 33
	v_readlane_b32 s42, v254, 34
	v_readlane_b32 s43, v254, 35
	v_readlane_b32 s44, v254, 36
	v_readlane_b32 s45, v254, 37
	v_readlane_b32 s46, v254, 38
	v_readlane_b32 s47, v254, 39
	v_readlane_b32 s49, v254, 41
	v_readlane_b32 s50, v254, 42
	v_readlane_b32 s51, v254, 43
	s_add_u32 s4, s48, s4
	v_mov_b32_e32 v61, v3
	v_lshrrev_b32_e32 v56, 16, v13
	v_add3_u32 v220, s80, v4, v60
	s_addc_u32 s5, s49, 0
	v_lshl_add_u64 v[178:179], s[40:41], 0, v[60:61]
	v_readlane_b32 s36, v253, 40
	v_lshrrev_b32_e32 v49, 16, v30
	v_lshrrev_b32_e32 v50, 16, v31
	v_lshrrev_b32_e32 v57, 16, v36
	v_lshrrev_b32_e32 v58, 16, v37
	v_lshrrev_b32_e32 v63, 16, v40
	v_lshrrev_b32_e32 v64, 16, v41
	ds_write_b128 v220, v[132:135]
	v_mul_u32_u24_e32 v4, 0x50, v55
	v_perm_b32 v152, v56, v13, s22
	v_mov_b32_e32 v13, v3
	v_readlane_b32 s37, v253, 41
	v_mov_b32_e32 v16, v3
	v_mov_b32_e32 v17, v3
	s_waitcnt lgkmcnt(0)
	s_barrier
	v_add3_u32 v222, s80, v4, v62
	v_xor_b32_e32 v20, 0x80000000, v46
	v_perm_b32 v146, v50, v31, s22
	v_perm_b32 v145, v49, v30, s22
	v_perm_b32 v154, v58, v37, s22
	v_perm_b32 v153, v57, v36, s22
	v_perm_b32 v158, v64, v41, s22
	v_perm_b32 v157, v63, v40, s22
	v_bfi_b32 v159, s23, v39, v39
	v_bfi_b32 v139, s23, v43, v43
	v_bfi_b32 v143, s23, v42, v42
	v_lshlrev_b32_e32 v221, 2, v51
	v_lshl_add_u64 v[176:177], s[4:5], 0, v[2:3]
	v_lshl_add_u64 v[180:181], s[36:37], 0, v[12:13]
	v_mov_b32_e32 v240, 1.0
	v_mov_b32_e32 v241, 1.0
	v_mov_b32_e32 v243, 1.0
	v_mov_b32_e32 v252, 1.0
	v_mov_b32_e32 v248, 1.0
	v_mov_b32_e32 v249, 1.0
	v_mov_b32_e32 v250, 1.0
	v_mov_b32_e32 v251, 1.0
	s_mov_b64 vcc, exec
	s_and_b64 exec, exec, s[0:1]
	global_load_dwordx4 v[248:251], v[180:181], off
	global_load_dwordx2 v[240:241], v[180:181], off offset:16
	global_load_dword v243, v[180:181], off offset:24
	global_load_dword v252, v[180:181], off offset:28
	s_mov_b64 exec, vcc
	v_mov_b32_e32 v2, v3
	v_mov_b32_e32 v4, v3
	v_mov_b32_e32 v5, v3
	v_mov_b32_e32 v6, v3
	v_mov_b32_e32 v7, v3
	v_mov_b32_e32 v8, v3
	v_mov_b32_e32 v9, v3
	v_mov_b32_e32 v10, v3
	v_mov_b32_e32 v11, v3
	v_mov_b32_e32 v12, v3
	v_mov_b32_e32 v14, v3
	v_mov_b32_e32 v15, v3
	v_mov_b64_e32 v[50:51], v[16:17]
	s_waitcnt lgkmcnt(2)
	v_lshrrev_b32_e32 v26, 16, v28
	v_lshrrev_b32_e32 v52, 16, v27
	v_lshrrev_b32_e32 v53, 16, v33
	v_lshrrev_b32_e32 v54, 16, v34
	v_mov_b64_e32 v[48:49], v[14:15]
	v_mov_b64_e32 v[46:47], v[12:13]
	v_mov_b64_e32 v[44:45], v[10:11]
	v_mov_b64_e32 v[42:43], v[8:9]
	v_mov_b64_e32 v[40:41], v[6:7]
	v_mov_b64_e32 v[38:39], v[4:5]
	v_mov_b64_e32 v[36:37], v[2:3]
	v_mov_b64_e32 v[18:19], v[16:17]
	s_mov_b32 s20, 0
	v_lshlrev_b32_e32 v206, 8, v55
	v_lshlrev_b32_e32 v212, 4, v65
	v_perm_b32 v144, v26, v28, s22
	v_bfi_b32 v147, s23, v29, v29
	v_perm_b32 v150, v54, v34, s22
	v_perm_b32 v149, v53, v33, s22
	v_perm_b32 v148, v52, v27, s22
	v_bfi_b32 v151, s23, v32, v32
	v_bfi_b32 v155, s23, v35, v35
	v_mov_b32_e32 v21, v20
	v_mov_b32_e32 v22, v20
	v_mov_b32_e32 v23, v20
	v_mov_b32_e32 v24, v20
	v_mov_b32_e32 v25, v20
	v_mov_b32_e32 v26, v20
	v_mov_b32_e32 v27, v20
	v_mov_b32_e32 v28, v20
	v_mov_b32_e32 v29, v20
	v_mov_b32_e32 v30, v20
	v_mov_b32_e32 v31, v20
	v_mov_b32_e32 v32, v20
	v_mov_b32_e32 v33, v20
	v_mov_b32_e32 v34, v20
	v_mov_b32_e32 v35, v20
	v_mov_b32_e32 v223, 0
	s_movk_i32 s27, 0x7f
	v_mov_b64_e32 v[16:17], v[14:15]
	v_mov_b64_e32 v[14:15], v[12:13]
	v_mov_b64_e32 v[12:13], v[10:11]
	v_mov_b64_e32 v[10:11], v[8:9]
	v_mov_b64_e32 v[8:9], v[6:7]
	v_mov_b64_e32 v[6:7], v[4:5]
	v_mov_b64_e32 v[4:5], v[2:3]
	v_readlane_b32 s38, v253, 42
	v_readlane_b32 s39, v253, 43
	v_readlane_b32 s40, v253, 44
	v_readlane_b32 s41, v253, 45
	v_readlane_b32 s42, v253, 46
	v_readlane_b32 s43, v253, 47
	v_readlane_b32 s44, v253, 48
	v_readlane_b32 s45, v253, 49
	v_readlane_b32 s46, v253, 50
	v_readlane_b32 s47, v253, 51
	v_readlane_b32 s48, v253, 52
	v_readlane_b32 s49, v253, 53
	v_readlane_b32 s50, v253, 54
	v_readlane_b32 s51, v253, 55

.LBB0_877:
	v_mov_b32_e32 v2, 1.0
	v_mov_b32_e32 v52, v240
	v_mov_b32_e32 v53, v241
	v_mov_b32_e32 v54, v243
	v_mov_b32_e32 v55, v252
	v_mov_b32_e32 v56, v248
	v_mov_b32_e32 v57, v249
	v_mov_b32_e32 v58, v250
	v_mov_b32_e32 v59, v251
	s_waitcnt vmcnt(4)
	v_and_b32_e32 v61, 0xffff0000, v116
	v_lshlrev_b32_e32 v60, 16, v116
	s_waitcnt lgkmcnt(2)
	v_pk_mul_f32 v[68:69], v[60:61], v[60:61]
	v_and_b32_e32 v63, 0xffff0000, v117
	v_lshlrev_b32_e32 v62, 16, v117
	v_pk_mul_f32 v[70:71], v[62:63], v[62:63]
	v_add_f32_e32 v68, v68, v69
	v_and_b32_e32 v65, 0xffff0000, v118
	v_lshlrev_b32_e32 v64, 16, v118
	v_add_f32_e32 v68, v70, v68
	v_pk_mul_f32 v[72:73], v[64:65], v[64:65]
	v_add_f32_e32 v68, v71, v68
	v_and_b32_e32 v67, 0xffff0000, v119
	v_lshlrev_b32_e32 v66, 16, v119
	v_add_f32_e32 v68, v72, v68
	v_pk_mul_f32 v[74:75], v[66:67], v[66:67]
	v_add_f32_e32 v68, v73, v68
	v_add_f32_e32 v68, v74, v68
	v_add_f32_e32 v68, v75, v68
	s_nop 1
	v_add_f32_dpp v68, v68, v68 quad_perm:[1,0,3,2] row_mask:0xf bank_mask:0xf
	s_nop 1
	v_add_f32_dpp v68, v68, v68 quad_perm:[2,3,0,1] row_mask:0xf bank_mask:0xf
	s_nop 1
	v_mov_b32_dpp v69, v68 row_half_mirror row_mask:0xf bank_mask:0xf
	s_and_saveexec_b64 s[4:5], s[0:1]
	s_cbranch_execz .LBB0_881
	s_waitcnt lgkmcnt(0)
	v_add_f32_e32 v2, v68, v69
	v_fmamk_f32 v2, v2, 0x3c800000, v160
	v_mul_f32_e32 v68, 0x4b800000, v2
	v_cmp_gt_f32_e32 vcc, s10, v2
	s_nop 1
	v_cndmask_b32_e32 v2, v2, v68, vcc
	v_rsq_f32_e32 v2, v2
	s_nop 0
	v_mul_f32_e32 v68, 0x45800000, v2
	v_cndmask_b32_e32 v2, v2, v68, vcc
.LBB0_881:
	s_or_b64 exec, exec, s[4:5]
	s_and_b32 s9, s28, 1
	s_lshl_b32 s4, s9, 15
	v_pk_mul_f32 v[60:61], v[2:3], v[60:61] op_sel_hi:[0,1]
	v_pk_mul_f32 v[62:63], v[2:3], v[62:63] op_sel_hi:[0,1]
	v_pk_mul_f32 v[64:65], v[2:3], v[64:65] op_sel_hi:[0,1]
	v_pk_mul_f32 v[66:67], v[2:3], v[66:67] op_sel_hi:[0,1]
	s_add_i32 s8, s4, 0
	s_waitcnt vmcnt(0)
	v_pk_mul_f32 v[60:61], v[56:57], v[60:61]
	v_pk_mul_f32 v[62:63], v[58:59], v[62:63]
	v_pk_mul_f32 v[64:65], v[52:53], v[64:65]
	v_pk_mul_f32 v[66:67], v[54:55], v[66:67]
	v_cvt_pk_bf16_f32 v60, v60, v61
	v_cvt_pk_bf16_f32 v61, v62, v63
	v_cvt_pk_bf16_f32 v62, v64, v65
	v_cvt_pk_bf16_f32 v63, v66, v67
	v_add3_u32 v2, s8, v201, v199
	ds_write_b128 v2, v[60:63]
	v_and_b32_e32 v61, 0xffff0000, v120
	v_lshlrev_b32_e32 v60, 16, v120
	s_waitcnt lgkmcnt(1)
	v_pk_mul_f32 v[68:69], v[60:61], v[60:61]
	v_and_b32_e32 v63, 0xffff0000, v121
	v_lshlrev_b32_e32 v62, 16, v121
	v_pk_mul_f32 v[70:71], v[62:63], v[62:63]
	v_add_f32_e32 v2, v68, v69
	v_and_b32_e32 v65, 0xffff0000, v122
	v_lshlrev_b32_e32 v64, 16, v122
	v_add_f32_e32 v2, v70, v2
	v_pk_mul_f32 v[72:73], v[64:65], v[64:65]
	v_add_f32_e32 v2, v71, v2
	v_and_b32_e32 v67, 0xffff0000, v123
	v_lshlrev_b32_e32 v66, 16, v123
	v_add_f32_e32 v2, v72, v2
	v_pk_mul_f32 v[74:75], v[66:67], v[66:67]
	v_add_f32_e32 v2, v73, v2
	v_add_f32_e32 v2, v74, v2
	v_add_f32_e32 v2, v75, v2
	s_nop 1
	v_add_f32_dpp v2, v2, v2 quad_perm:[1,0,3,2] row_mask:0xf bank_mask:0xf
	s_nop 1
	v_add_f32_dpp v69, v2, v2 quad_perm:[2,3,0,1] row_mask:0xf bank_mask:0xf
	s_nop 1
	v_mov_b32_dpp v70, v69 row_half_mirror row_mask:0xf bank_mask:0xf
	v_mov_b32_e32 v2, 1.0
	v_mov_b32_e32 v68, 1.0
	s_and_saveexec_b64 s[4:5], s[0:1]
	s_cbranch_execz .LBB0_883
	s_waitcnt lgkmcnt(0)
	v_add_f32_e32 v68, v69, v70
	v_fmamk_f32 v68, v68, 0x3c800000, v160
	v_mul_f32_e32 v69, 0x4b800000, v68
	v_cmp_gt_f32_e32 vcc, s10, v68
	s_nop 1
	v_cndmask_b32_e32 v68, v68, v69, vcc
	v_rsq_f32_e32 v68, v68
	s_nop 0
	v_mul_f32_e32 v69, 0x45800000, v68
	v_cndmask_b32_e32 v68, v68, v69, vcc
.LBB0_883:
	s_or_b64 exec, exec, s[4:5]
	v_pk_mul_f32 v[60:61], v[68:69], v[60:61] op_sel_hi:[0,1]
	v_pk_mul_f32 v[62:63], v[68:69], v[62:63] op_sel_hi:[0,1]
	v_pk_mul_f32 v[64:65], v[68:69], v[64:65] op_sel_hi:[0,1]
	v_pk_mul_f32 v[66:67], v[68:69], v[66:67] op_sel_hi:[0,1]
	v_pk_mul_f32 v[60:61], v[56:57], v[60:61]
	v_pk_mul_f32 v[62:63], v[58:59], v[62:63]
	v_pk_mul_f32 v[64:65], v[52:53], v[64:65]
	v_pk_mul_f32 v[66:67], v[54:55], v[66:67]
	v_cvt_pk_bf16_f32 v60, v60, v61
	v_cvt_pk_bf16_f32 v61, v62, v63
	v_cvt_pk_bf16_f32 v62, v64, v65
	v_cvt_pk_bf16_f32 v63, v66, v67
	v_add3_u32 v64, s8, v203, v202
	ds_write_b128 v64, v[60:63]
	v_and_b32_e32 v61, 0xffff0000, v124
	v_lshlrev_b32_e32 v60, 16, v124
	v_pk_mul_f32 v[68:69], v[60:61], v[60:61]
	v_and_b32_e32 v63, 0xffff0000, v125
	v_lshlrev_b32_e32 v62, 16, v125
	s_waitcnt lgkmcnt(1)
	v_pk_mul_f32 v[70:71], v[62:63], v[62:63]
	v_add_f32_e32 v68, v68, v69
	v_and_b32_e32 v65, 0xffff0000, v126
	v_lshlrev_b32_e32 v64, 16, v126
	v_add_f32_e32 v68, v70, v68
	v_pk_mul_f32 v[72:73], v[64:65], v[64:65]
	v_add_f32_e32 v68, v71, v68
	v_and_b32_e32 v67, 0xffff0000, v127
	v_lshlrev_b32_e32 v66, 16, v127
	v_add_f32_e32 v68, v72, v68
	v_pk_mul_f32 v[74:75], v[66:67], v[66:67]
	v_add_f32_e32 v68, v73, v68
	v_add_f32_e32 v68, v74, v68
	v_add_f32_e32 v68, v75, v68
	s_nop 1
	v_add_f32_dpp v68, v68, v68 quad_perm:[1,0,3,2] row_mask:0xf bank_mask:0xf
	s_nop 1
	v_add_f32_dpp v68, v68, v68 quad_perm:[2,3,0,1] row_mask:0xf bank_mask:0xf
	s_nop 1
	v_mov_b32_dpp v69, v68 row_half_mirror row_mask:0xf bank_mask:0xf
	s_and_saveexec_b64 s[4:5], s[0:1]
	s_cbranch_execz .LBB0_885
	s_waitcnt lgkmcnt(0)
	v_add_f32_e32 v2, v68, v69
	v_fmamk_f32 v2, v2, 0x3c800000, v160
	v_mul_f32_e32 v68, 0x4b800000, v2
	v_cmp_gt_f32_e32 vcc, s10, v2
	s_nop 1
	v_cndmask_b32_e32 v2, v2, v68, vcc
	v_rsq_f32_e32 v2, v2
	s_nop 0
	v_mul_f32_e32 v68, 0x45800000, v2
	v_cndmask_b32_e32 v2, v2, v68, vcc
.LBB0_885:
	s_or_b64 exec, exec, s[4:5]
	v_pk_mul_f32 v[60:61], v[2:3], v[60:61] op_sel_hi:[0,1]
	v_pk_mul_f32 v[62:63], v[2:3], v[62:63] op_sel_hi:[0,1]
	v_pk_mul_f32 v[64:65], v[2:3], v[64:65] op_sel_hi:[0,1]
	v_pk_mul_f32 v[66:67], v[2:3], v[66:67] op_sel_hi:[0,1]
	v_pk_mul_f32 v[60:61], v[56:57], v[60:61]
	v_pk_mul_f32 v[62:63], v[58:59], v[62:63]
	v_pk_mul_f32 v[64:65], v[52:53], v[64:65]
	v_pk_mul_f32 v[66:67], v[54:55], v[66:67]
	v_cvt_pk_bf16_f32 v60, v60, v61
	v_cvt_pk_bf16_f32 v61, v62, v63
	v_cvt_pk_bf16_f32 v62, v64, v65
	v_cvt_pk_bf16_f32 v63, v66, v67
	v_add3_u32 v2, s8, v205, v204
	ds_write_b128 v2, v[60:63]
	v_and_b32_e32 v61, 0xffff0000, v128
	v_lshlrev_b32_e32 v60, 16, v128
	s_waitcnt lgkmcnt(1)
	v_pk_mul_f32 v[68:69], v[60:61], v[60:61]
	v_and_b32_e32 v63, 0xffff0000, v129
	v_lshlrev_b32_e32 v62, 16, v129
	v_pk_mul_f32 v[70:71], v[62:63], v[62:63]
	v_add_f32_e32 v2, v68, v69
	v_and_b32_e32 v65, 0xffff0000, v130
	v_lshlrev_b32_e32 v64, 16, v130
	v_add_f32_e32 v2, v70, v2
	v_pk_mul_f32 v[72:73], v[64:65], v[64:65]
	v_add_f32_e32 v2, v71, v2
	v_and_b32_e32 v67, 0xffff0000, v131
	v_lshlrev_b32_e32 v66, 16, v131
	v_add_f32_e32 v2, v72, v2
	v_pk_mul_f32 v[74:75], v[66:67], v[66:67]
	v_add_f32_e32 v2, v73, v2
	v_add_f32_e32 v2, v74, v2
	v_add_f32_e32 v2, v75, v2
	s_nop 1
	v_add_f32_dpp v2, v2, v2 quad_perm:[1,0,3,2] row_mask:0xf bank_mask:0xf
	s_nop 1
	v_add_f32_dpp v68, v2, v2 quad_perm:[2,3,0,1] row_mask:0xf bank_mask:0xf
	s_nop 1
	v_mov_b32_dpp v69, v68 row_half_mirror row_mask:0xf bank_mask:0xf
	v_mov_b32_e32 v2, 1.0
	s_and_saveexec_b64 s[4:5], s[0:1]
	s_cbranch_execz .LBB0_887
	s_waitcnt lgkmcnt(0)
	v_add_f32_e32 v2, v68, v69
	v_fmamk_f32 v2, v2, 0x3c800000, v160
	v_mul_f32_e32 v68, 0x4b800000, v2
	v_cmp_gt_f32_e32 vcc, s10, v2
	s_nop 1
	v_cndmask_b32_e32 v2, v2, v68, vcc
	v_rsq_f32_e32 v2, v2
	s_nop 0
	v_mul_f32_e32 v68, 0x45800000, v2
	v_cndmask_b32_e32 v2, v2, v68, vcc
